# final f32 output stores non-temporal
# baseline (speedup 1.0000x reference)
; __device__ __forceinline__ float bflo(unsigned u) { return __uint_as_float(u << 16); }
; __device__ __forceinline__ float bfhi(unsigned u) { return __uint_as_float(u & 0xffff0000u); }
; __device__ __forceinline__ unsigned pk2(float lo, float hi) { f32x2_t v = {lo, hi}; bf16x2_t b = __builtin_convertvector(v, bf16x2_t); return __builtin_bit_cast(unsigned, b); }
;     __device__ __forceinline__ void operator()(const f32x4 (&acc)[2][2][4][2], const pg8::Unit& u, int wr, int wc, int fr, int fq) const {
;     ...
;                     f32x4 x0, x1;
;                     if (xin) { x0 = *(const f32x4*)(xin + off); x1 = *(const f32x4*)(xin + off + 4); }
;                     else { const v4u xv = *(const v4u*)(xb + off); x0 = (f32x4){bflo(xv.x), bfhi(xv.x), bflo(xv.y), bfhi(xv.y)}; x1 = (f32x4){bflo(xv.z), bfhi(xv.z), bflo(xv.w), bfhi(xv.w)}; }
;                     const f32x4 n0 = x0 + acc[ai][bj][m][0], n1 = x1 + acc[ai][bj][m][1];
;                     if (xout) { *(f32x4*)(xout + off) = n0; *(f32x4*)(xout + off + 4) = n1; }
;                     else *(v4u*)(xb + off) = (v4u){pk2(n0[0], n0[1]), pk2(n0[2], n0[3]), pk2(n1[0], n1[1]), pk2(n1[2], n1[3])};
.LBB0_1385:
	s_waitcnt vmcnt(0)
	v_pk_add_f32 v[122:123], v[122:123], v[130:131]
	v_cndmask_b32_e64 v130, 0, 1, s[36:37]
	v_pk_add_f32 v[128:129], v[128:129], v[136:137]
	v_pk_add_f32 v[126:127], v[126:127], v[134:135]
	v_pk_add_f32 v[124:125], v[124:125], v[132:133]
	v_cmp_ne_u32_e64 s[6:7], 1, v130
	s_andn2_b64 vcc, exec, s[36:37]
	v_lshl_add_u64 v[182:183], v[178:179], 2, s[18:19]
	s_cbranch_vccnz .LBB0_1513
	global_store_dwordx4 v[182:183], v[126:129], off nt
	global_store_dwordx4 v[182:183], v[122:125], off offset:16 nt
	s_cbranch_execnz .LBB0_1388

; __device__ __forceinline__ float bflo(unsigned u) { return __uint_as_float(u << 16); }
; __device__ __forceinline__ float bfhi(unsigned u) { return __uint_as_float(u & 0xffff0000u); }
; __device__ __forceinline__ unsigned pk2(float lo, float hi) { f32x2_t v = {lo, hi}; bf16x2_t b = __builtin_convertvector(v, bf16x2_t); return __builtin_bit_cast(unsigned, b); }
;     __device__ __forceinline__ void operator()(const f32x4 (&acc)[2][2][4][2], const pg8::Unit& u, int wr, int wc, int fr, int fq) const {
;     ...
;                     f32x4 x0, x1;
;                     if (xin) { x0 = *(const f32x4*)(xin + off); x1 = *(const f32x4*)(xin + off + 4); }
;                     else { const v4u xv = *(const v4u*)(xb + off); x0 = (f32x4){bflo(xv.x), bfhi(xv.x), bflo(xv.y), bfhi(xv.y)}; x1 = (f32x4){bflo(xv.z), bfhi(xv.z), bflo(xv.w), bfhi(xv.w)}; }
;                     const f32x4 n0 = x0 + acc[ai][bj][m][0], n1 = x1 + acc[ai][bj][m][1];
;                     if (xout) { *(f32x4*)(xout + off) = n0; *(f32x4*)(xout + off + 4) = n1; }
;                     else *(v4u*)(xb + off) = (v4u){pk2(n0[0], n0[1]), pk2(n0[2], n0[3]), pk2(n1[0], n1[1]), pk2(n1[2], n1[3])};
.LBB0_1391:
	s_waitcnt vmcnt(0)
	v_pk_add_f32 v[120:121], v[120:121], v[136:137]
	v_pk_add_f32 v[118:119], v[118:119], v[134:135]
	v_pk_add_f32 v[116:117], v[116:117], v[132:133]
	s_and_b64 vcc, exec, s[6:7]
	v_pk_add_f32 v[114:115], v[114:115], v[130:131]
	s_cbranch_vccnz .LBB0_1515
	global_store_dwordx4 v[182:183], v[118:121], off offset:512 nt
	global_store_dwordx4 v[182:183], v[114:117], off offset:528 nt
	s_cbranch_execnz .LBB0_1394

; __device__ __forceinline__ float bflo(unsigned u) { return __uint_as_float(u << 16); }
; __device__ __forceinline__ float bfhi(unsigned u) { return __uint_as_float(u & 0xffff0000u); }
; __device__ __forceinline__ unsigned pk2(float lo, float hi) { f32x2_t v = {lo, hi}; bf16x2_t b = __builtin_convertvector(v, bf16x2_t); return __builtin_bit_cast(unsigned, b); }
;     __device__ __forceinline__ void operator()(const f32x4 (&acc)[2][2][4][2], const pg8::Unit& u, int wr, int wc, int fr, int fq) const {
;     ...
;                     f32x4 x0, x1;
;                     if (xin) { x0 = *(const f32x4*)(xin + off); x1 = *(const f32x4*)(xin + off + 4); }
;                     else { const v4u xv = *(const v4u*)(xb + off); x0 = (f32x4){bflo(xv.x), bfhi(xv.x), bflo(xv.y), bfhi(xv.y)}; x1 = (f32x4){bflo(xv.z), bfhi(xv.z), bflo(xv.w), bfhi(xv.w)}; }
;                     const f32x4 n0 = x0 + acc[ai][bj][m][0], n1 = x1 + acc[ai][bj][m][1];
;                     if (xout) { *(f32x4*)(xout + off) = n0; *(f32x4*)(xout + off + 4) = n1; }
;                     else *(v4u*)(xb + off) = (v4u){pk2(n0[0], n0[1]), pk2(n0[2], n0[3]), pk2(n1[0], n1[1]), pk2(n1[2], n1[3])};
.LBB0_1401:
	s_waitcnt vmcnt(0)
	v_pk_add_f32 v[112:113], v[112:113], v[120:121]
	v_pk_add_f32 v[110:111], v[110:111], v[118:119]
	v_pk_add_f32 v[108:109], v[108:109], v[116:117]
	v_pk_add_f32 v[106:107], v[106:107], v[114:115]
	s_and_b64 vcc, exec, s[6:7]
	v_lshl_add_u64 v[126:127], v[124:125], 2, s[18:19]
	s_cbranch_vccnz .LBB0_1517
	global_store_dwordx4 v[126:127], v[110:113], off nt
	global_store_dwordx4 v[126:127], v[106:109], off offset:16 nt
	s_cbranch_execnz .LBB0_1404

; __device__ __forceinline__ float bflo(unsigned u) { return __uint_as_float(u << 16); }
; __device__ __forceinline__ float bfhi(unsigned u) { return __uint_as_float(u & 0xffff0000u); }
; __device__ __forceinline__ unsigned pk2(float lo, float hi) { f32x2_t v = {lo, hi}; bf16x2_t b = __builtin_convertvector(v, bf16x2_t); return __builtin_bit_cast(unsigned, b); }
;     __device__ __forceinline__ void operator()(const f32x4 (&acc)[2][2][4][2], const pg8::Unit& u, int wr, int wc, int fr, int fq) const {
;     ...
;                     f32x4 x0, x1;
;                     if (xin) { x0 = *(const f32x4*)(xin + off); x1 = *(const f32x4*)(xin + off + 4); }
;                     else { const v4u xv = *(const v4u*)(xb + off); x0 = (f32x4){bflo(xv.x), bfhi(xv.x), bflo(xv.y), bfhi(xv.y)}; x1 = (f32x4){bflo(xv.z), bfhi(xv.z), bflo(xv.w), bfhi(xv.w)}; }
;                     const f32x4 n0 = x0 + acc[ai][bj][m][0], n1 = x1 + acc[ai][bj][m][1];
;                     if (xout) { *(f32x4*)(xout + off) = n0; *(f32x4*)(xout + off + 4) = n1; }
;                     else *(v4u*)(xb + off) = (v4u){pk2(n0[0], n0[1]), pk2(n0[2], n0[3]), pk2(n1[0], n1[1]), pk2(n1[2], n1[3])};
.LBB0_1407:
	s_waitcnt vmcnt(0)
	v_pk_add_f32 v[104:105], v[104:105], v[120:121]
	v_pk_add_f32 v[102:103], v[102:103], v[118:119]
	v_pk_add_f32 v[100:101], v[100:101], v[116:117]
	s_and_b64 vcc, exec, s[6:7]
	v_pk_add_f32 v[98:99], v[98:99], v[114:115]
	s_cbranch_vccnz .LBB0_1519
	global_store_dwordx4 v[126:127], v[102:105], off offset:512 nt
	global_store_dwordx4 v[126:127], v[98:101], off offset:528 nt
	s_cbranch_execnz .LBB0_1410

; __device__ __forceinline__ float bflo(unsigned u) { return __uint_as_float(u << 16); }
; __device__ __forceinline__ float bfhi(unsigned u) { return __uint_as_float(u & 0xffff0000u); }
; __device__ __forceinline__ unsigned pk2(float lo, float hi) { f32x2_t v = {lo, hi}; bf16x2_t b = __builtin_convertvector(v, bf16x2_t); return __builtin_bit_cast(unsigned, b); }
;     __device__ __forceinline__ void operator()(const f32x4 (&acc)[2][2][4][2], const pg8::Unit& u, int wr, int wc, int fr, int fq) const {
;     ...
;                     f32x4 x0, x1;
;                     if (xin) { x0 = *(const f32x4*)(xin + off); x1 = *(const f32x4*)(xin + off + 4); }
;                     else { const v4u xv = *(const v4u*)(xb + off); x0 = (f32x4){bflo(xv.x), bfhi(xv.x), bflo(xv.y), bfhi(xv.y)}; x1 = (f32x4){bflo(xv.z), bfhi(xv.z), bflo(xv.w), bfhi(xv.w)}; }
;                     const f32x4 n0 = x0 + acc[ai][bj][m][0], n1 = x1 + acc[ai][bj][m][1];
;                     if (xout) { *(f32x4*)(xout + off) = n0; *(f32x4*)(xout + off + 4) = n1; }
;                     else *(v4u*)(xb + off) = (v4u){pk2(n0[0], n0[1]), pk2(n0[2], n0[3]), pk2(n1[0], n1[1]), pk2(n1[2], n1[3])};
.LBB0_1417:
	s_waitcnt vmcnt(0)
	v_pk_add_f32 v[96:97], v[96:97], v[104:105]
	v_pk_add_f32 v[94:95], v[94:95], v[102:103]
	v_pk_add_f32 v[92:93], v[92:93], v[100:101]
	v_pk_add_f32 v[90:91], v[90:91], v[98:99]
	s_and_b64 vcc, exec, s[6:7]
	v_lshl_add_u64 v[110:111], v[108:109], 2, s[18:19]
	s_cbranch_vccnz .LBB0_1521
	global_store_dwordx4 v[110:111], v[94:97], off nt
	global_store_dwordx4 v[110:111], v[90:93], off offset:16 nt
	s_cbranch_execnz .LBB0_1420

; __device__ __forceinline__ float bflo(unsigned u) { return __uint_as_float(u << 16); }
; __device__ __forceinline__ float bfhi(unsigned u) { return __uint_as_float(u & 0xffff0000u); }
; __device__ __forceinline__ unsigned pk2(float lo, float hi) { f32x2_t v = {lo, hi}; bf16x2_t b = __builtin_convertvector(v, bf16x2_t); return __builtin_bit_cast(unsigned, b); }
;     __device__ __forceinline__ void operator()(const f32x4 (&acc)[2][2][4][2], const pg8::Unit& u, int wr, int wc, int fr, int fq) const {
;     ...
;                     f32x4 x0, x1;
;                     if (xin) { x0 = *(const f32x4*)(xin + off); x1 = *(const f32x4*)(xin + off + 4); }
;                     else { const v4u xv = *(const v4u*)(xb + off); x0 = (f32x4){bflo(xv.x), bfhi(xv.x), bflo(xv.y), bfhi(xv.y)}; x1 = (f32x4){bflo(xv.z), bfhi(xv.z), bflo(xv.w), bfhi(xv.w)}; }
;                     const f32x4 n0 = x0 + acc[ai][bj][m][0], n1 = x1 + acc[ai][bj][m][1];
;                     if (xout) { *(f32x4*)(xout + off) = n0; *(f32x4*)(xout + off + 4) = n1; }
;                     else *(v4u*)(xb + off) = (v4u){pk2(n0[0], n0[1]), pk2(n0[2], n0[3]), pk2(n1[0], n1[1]), pk2(n1[2], n1[3])};
.LBB0_1423:
	s_waitcnt vmcnt(0)
	v_pk_add_f32 v[88:89], v[88:89], v[104:105]
	v_pk_add_f32 v[86:87], v[86:87], v[102:103]
	v_pk_add_f32 v[84:85], v[84:85], v[100:101]
	s_and_b64 vcc, exec, s[6:7]
	v_pk_add_f32 v[82:83], v[82:83], v[98:99]
	s_cbranch_vccnz .LBB0_1523
	global_store_dwordx4 v[110:111], v[86:89], off offset:512 nt
	global_store_dwordx4 v[110:111], v[82:85], off offset:528 nt
	s_cbranch_execnz .LBB0_1426

; __device__ __forceinline__ float bflo(unsigned u) { return __uint_as_float(u << 16); }
; __device__ __forceinline__ float bfhi(unsigned u) { return __uint_as_float(u & 0xffff0000u); }
; __device__ __forceinline__ unsigned pk2(float lo, float hi) { f32x2_t v = {lo, hi}; bf16x2_t b = __builtin_convertvector(v, bf16x2_t); return __builtin_bit_cast(unsigned, b); }
;     __device__ __forceinline__ void operator()(const f32x4 (&acc)[2][2][4][2], const pg8::Unit& u, int wr, int wc, int fr, int fq) const {
;     ...
;                     f32x4 x0, x1;
;                     if (xin) { x0 = *(const f32x4*)(xin + off); x1 = *(const f32x4*)(xin + off + 4); }
;                     else { const v4u xv = *(const v4u*)(xb + off); x0 = (f32x4){bflo(xv.x), bfhi(xv.x), bflo(xv.y), bfhi(xv.y)}; x1 = (f32x4){bflo(xv.z), bfhi(xv.z), bflo(xv.w), bfhi(xv.w)}; }
;                     const f32x4 n0 = x0 + acc[ai][bj][m][0], n1 = x1 + acc[ai][bj][m][1];
;                     if (xout) { *(f32x4*)(xout + off) = n0; *(f32x4*)(xout + off + 4) = n1; }
;                     else *(v4u*)(xb + off) = (v4u){pk2(n0[0], n0[1]), pk2(n0[2], n0[3]), pk2(n1[0], n1[1]), pk2(n1[2], n1[3])};
.LBB0_1433:
	s_waitcnt vmcnt(0)
	v_pk_add_f32 v[80:81], v[80:81], v[88:89]
	v_pk_add_f32 v[78:79], v[78:79], v[86:87]
	v_pk_add_f32 v[76:77], v[76:77], v[84:85]
	v_pk_add_f32 v[74:75], v[74:75], v[82:83]
	s_and_b64 vcc, exec, s[6:7]
	v_lshl_add_u64 v[94:95], v[92:93], 2, s[18:19]
	s_cbranch_vccnz .LBB0_1525
	global_store_dwordx4 v[94:95], v[78:81], off nt
	global_store_dwordx4 v[94:95], v[74:77], off offset:16 nt
	s_cbranch_execnz .LBB0_1436

; __device__ __forceinline__ float bflo(unsigned u) { return __uint_as_float(u << 16); }
; __device__ __forceinline__ float bfhi(unsigned u) { return __uint_as_float(u & 0xffff0000u); }
; __device__ __forceinline__ unsigned pk2(float lo, float hi) { f32x2_t v = {lo, hi}; bf16x2_t b = __builtin_convertvector(v, bf16x2_t); return __builtin_bit_cast(unsigned, b); }
;     __device__ __forceinline__ void operator()(const f32x4 (&acc)[2][2][4][2], const pg8::Unit& u, int wr, int wc, int fr, int fq) const {
;     ...
;                     f32x4 x0, x1;
;                     if (xin) { x0 = *(const f32x4*)(xin + off); x1 = *(const f32x4*)(xin + off + 4); }
;                     else { const v4u xv = *(const v4u*)(xb + off); x0 = (f32x4){bflo(xv.x), bfhi(xv.x), bflo(xv.y), bfhi(xv.y)}; x1 = (f32x4){bflo(xv.z), bfhi(xv.z), bflo(xv.w), bfhi(xv.w)}; }
;                     const f32x4 n0 = x0 + acc[ai][bj][m][0], n1 = x1 + acc[ai][bj][m][1];
;                     if (xout) { *(f32x4*)(xout + off) = n0; *(f32x4*)(xout + off + 4) = n1; }
;                     else *(v4u*)(xb + off) = (v4u){pk2(n0[0], n0[1]), pk2(n0[2], n0[3]), pk2(n1[0], n1[1]), pk2(n1[2], n1[3])};
.LBB0_1439:
	s_waitcnt vmcnt(0)
	v_pk_add_f32 v[72:73], v[72:73], v[88:89]
	v_pk_add_f32 v[70:71], v[70:71], v[86:87]
	v_pk_add_f32 v[68:69], v[68:69], v[84:85]
	s_and_b64 vcc, exec, s[6:7]
	v_pk_add_f32 v[66:67], v[66:67], v[82:83]
	s_cbranch_vccnz .LBB0_1527
	global_store_dwordx4 v[94:95], v[70:73], off offset:512 nt
	global_store_dwordx4 v[94:95], v[66:69], off offset:528 nt
	s_cbranch_execnz .LBB0_1442

; __device__ __forceinline__ float bflo(unsigned u) { return __uint_as_float(u << 16); }
; __device__ __forceinline__ float bfhi(unsigned u) { return __uint_as_float(u & 0xffff0000u); }
; __device__ __forceinline__ unsigned pk2(float lo, float hi) { f32x2_t v = {lo, hi}; bf16x2_t b = __builtin_convertvector(v, bf16x2_t); return __builtin_bit_cast(unsigned, b); }
;     __device__ __forceinline__ void operator()(const f32x4 (&acc)[2][2][4][2], const pg8::Unit& u, int wr, int wc, int fr, int fq) const {
;     ...
;                     f32x4 x0, x1;
;                     if (xin) { x0 = *(const f32x4*)(xin + off); x1 = *(const f32x4*)(xin + off + 4); }
;                     else { const v4u xv = *(const v4u*)(xb + off); x0 = (f32x4){bflo(xv.x), bfhi(xv.x), bflo(xv.y), bfhi(xv.y)}; x1 = (f32x4){bflo(xv.z), bfhi(xv.z), bflo(xv.w), bfhi(xv.w)}; }
;                     const f32x4 n0 = x0 + acc[ai][bj][m][0], n1 = x1 + acc[ai][bj][m][1];
;                     if (xout) { *(f32x4*)(xout + off) = n0; *(f32x4*)(xout + off + 4) = n1; }
;                     else *(v4u*)(xb + off) = (v4u){pk2(n0[0], n0[1]), pk2(n0[2], n0[3]), pk2(n1[0], n1[1]), pk2(n1[2], n1[3])};
.LBB0_1449:
	s_waitcnt vmcnt(0)
	v_pk_add_f32 v[64:65], v[64:65], v[72:73]
	v_pk_add_f32 v[62:63], v[62:63], v[70:71]
	v_pk_add_f32 v[60:61], v[60:61], v[68:69]
	v_pk_add_f32 v[58:59], v[58:59], v[66:67]
	s_and_b64 vcc, exec, s[6:7]
	v_lshl_add_u64 v[78:79], v[76:77], 2, s[18:19]
	s_cbranch_vccnz .LBB0_1529
	global_store_dwordx4 v[78:79], v[62:65], off nt
	global_store_dwordx4 v[78:79], v[58:61], off offset:16 nt
	s_cbranch_execnz .LBB0_1452

; __device__ __forceinline__ float bflo(unsigned u) { return __uint_as_float(u << 16); }
; __device__ __forceinline__ float bfhi(unsigned u) { return __uint_as_float(u & 0xffff0000u); }
; __device__ __forceinline__ unsigned pk2(float lo, float hi) { f32x2_t v = {lo, hi}; bf16x2_t b = __builtin_convertvector(v, bf16x2_t); return __builtin_bit_cast(unsigned, b); }
;     __device__ __forceinline__ void operator()(const f32x4 (&acc)[2][2][4][2], const pg8::Unit& u, int wr, int wc, int fr, int fq) const {
;     ...
;                     f32x4 x0, x1;
;                     if (xin) { x0 = *(const f32x4*)(xin + off); x1 = *(const f32x4*)(xin + off + 4); }
;                     else { const v4u xv = *(const v4u*)(xb + off); x0 = (f32x4){bflo(xv.x), bfhi(xv.x), bflo(xv.y), bfhi(xv.y)}; x1 = (f32x4){bflo(xv.z), bfhi(xv.z), bflo(xv.w), bfhi(xv.w)}; }
;                     const f32x4 n0 = x0 + acc[ai][bj][m][0], n1 = x1 + acc[ai][bj][m][1];
;                     if (xout) { *(f32x4*)(xout + off) = n0; *(f32x4*)(xout + off + 4) = n1; }
;                     else *(v4u*)(xb + off) = (v4u){pk2(n0[0], n0[1]), pk2(n0[2], n0[3]), pk2(n1[0], n1[1]), pk2(n1[2], n1[3])};
.LBB0_1455:
	s_waitcnt vmcnt(0)
	v_pk_add_f32 v[56:57], v[56:57], v[72:73]
	v_pk_add_f32 v[54:55], v[54:55], v[70:71]
	v_pk_add_f32 v[52:53], v[52:53], v[68:69]
	s_and_b64 vcc, exec, s[6:7]
	v_pk_add_f32 v[50:51], v[50:51], v[66:67]
	s_cbranch_vccnz .LBB0_1531
	global_store_dwordx4 v[78:79], v[54:57], off offset:512 nt
	global_store_dwordx4 v[78:79], v[50:53], off offset:528 nt
	s_cbranch_execnz .LBB0_1458

; __device__ __forceinline__ float bflo(unsigned u) { return __uint_as_float(u << 16); }
; __device__ __forceinline__ float bfhi(unsigned u) { return __uint_as_float(u & 0xffff0000u); }
; __device__ __forceinline__ unsigned pk2(float lo, float hi) { f32x2_t v = {lo, hi}; bf16x2_t b = __builtin_convertvector(v, bf16x2_t); return __builtin_bit_cast(unsigned, b); }
;     __device__ __forceinline__ void operator()(const f32x4 (&acc)[2][2][4][2], const pg8::Unit& u, int wr, int wc, int fr, int fq) const {
;     ...
;                     f32x4 x0, x1;
;                     if (xin) { x0 = *(const f32x4*)(xin + off); x1 = *(const f32x4*)(xin + off + 4); }
;                     else { const v4u xv = *(const v4u*)(xb + off); x0 = (f32x4){bflo(xv.x), bfhi(xv.x), bflo(xv.y), bfhi(xv.y)}; x1 = (f32x4){bflo(xv.z), bfhi(xv.z), bflo(xv.w), bfhi(xv.w)}; }
;                     const f32x4 n0 = x0 + acc[ai][bj][m][0], n1 = x1 + acc[ai][bj][m][1];
;                     if (xout) { *(f32x4*)(xout + off) = n0; *(f32x4*)(xout + off + 4) = n1; }
;                     else *(v4u*)(xb + off) = (v4u){pk2(n0[0], n0[1]), pk2(n0[2], n0[3]), pk2(n1[0], n1[1]), pk2(n1[2], n1[3])};
.LBB0_1465:
	s_waitcnt vmcnt(0)
	v_pk_add_f32 v[48:49], v[48:49], v[56:57]
	v_pk_add_f32 v[46:47], v[46:47], v[54:55]
	v_pk_add_f32 v[44:45], v[44:45], v[52:53]
	v_pk_add_f32 v[42:43], v[42:43], v[50:51]
	s_and_b64 vcc, exec, s[6:7]
	v_lshl_add_u64 v[62:63], v[60:61], 2, s[18:19]
	s_cbranch_vccnz .LBB0_1533
	global_store_dwordx4 v[62:63], v[46:49], off nt
	global_store_dwordx4 v[62:63], v[42:45], off offset:16 nt
	s_cbranch_execnz .LBB0_1468

; __device__ __forceinline__ float bflo(unsigned u) { return __uint_as_float(u << 16); }
; __device__ __forceinline__ float bfhi(unsigned u) { return __uint_as_float(u & 0xffff0000u); }
; __device__ __forceinline__ unsigned pk2(float lo, float hi) { f32x2_t v = {lo, hi}; bf16x2_t b = __builtin_convertvector(v, bf16x2_t); return __builtin_bit_cast(unsigned, b); }
;     __device__ __forceinline__ void operator()(const f32x4 (&acc)[2][2][4][2], const pg8::Unit& u, int wr, int wc, int fr, int fq) const {
;     ...
;                     f32x4 x0, x1;
;                     if (xin) { x0 = *(const f32x4*)(xin + off); x1 = *(const f32x4*)(xin + off + 4); }
;                     else { const v4u xv = *(const v4u*)(xb + off); x0 = (f32x4){bflo(xv.x), bfhi(xv.x), bflo(xv.y), bfhi(xv.y)}; x1 = (f32x4){bflo(xv.z), bfhi(xv.z), bflo(xv.w), bfhi(xv.w)}; }
;                     const f32x4 n0 = x0 + acc[ai][bj][m][0], n1 = x1 + acc[ai][bj][m][1];
;                     if (xout) { *(f32x4*)(xout + off) = n0; *(f32x4*)(xout + off + 4) = n1; }
;                     else *(v4u*)(xb + off) = (v4u){pk2(n0[0], n0[1]), pk2(n0[2], n0[3]), pk2(n1[0], n1[1]), pk2(n1[2], n1[3])};
.LBB0_1471:
	s_waitcnt vmcnt(0)
	v_pk_add_f32 v[40:41], v[40:41], v[56:57]
	v_pk_add_f32 v[38:39], v[38:39], v[54:55]
	v_pk_add_f32 v[36:37], v[36:37], v[52:53]
	s_and_b64 vcc, exec, s[6:7]
	v_pk_add_f32 v[34:35], v[34:35], v[50:51]
	s_cbranch_vccnz .LBB0_1535
	global_store_dwordx4 v[62:63], v[38:41], off offset:512 nt
	global_store_dwordx4 v[62:63], v[34:37], off offset:528 nt
	s_cbranch_execnz .LBB0_1474

; __device__ __forceinline__ float bflo(unsigned u) { return __uint_as_float(u << 16); }
; __device__ __forceinline__ float bfhi(unsigned u) { return __uint_as_float(u & 0xffff0000u); }
; __device__ __forceinline__ unsigned pk2(float lo, float hi) { f32x2_t v = {lo, hi}; bf16x2_t b = __builtin_convertvector(v, bf16x2_t); return __builtin_bit_cast(unsigned, b); }
;     __device__ __forceinline__ void operator()(const f32x4 (&acc)[2][2][4][2], const pg8::Unit& u, int wr, int wc, int fr, int fq) const {
;     ...
;                     f32x4 x0, x1;
;                     if (xin) { x0 = *(const f32x4*)(xin + off); x1 = *(const f32x4*)(xin + off + 4); }
;                     else { const v4u xv = *(const v4u*)(xb + off); x0 = (f32x4){bflo(xv.x), bfhi(xv.x), bflo(xv.y), bfhi(xv.y)}; x1 = (f32x4){bflo(xv.z), bfhi(xv.z), bflo(xv.w), bfhi(xv.w)}; }
;                     const f32x4 n0 = x0 + acc[ai][bj][m][0], n1 = x1 + acc[ai][bj][m][1];
;                     if (xout) { *(f32x4*)(xout + off) = n0; *(f32x4*)(xout + off + 4) = n1; }
;                     else *(v4u*)(xb + off) = (v4u){pk2(n0[0], n0[1]), pk2(n0[2], n0[3]), pk2(n1[0], n1[1]), pk2(n1[2], n1[3])};
.LBB0_1481:
	s_waitcnt vmcnt(0)
	v_pk_add_f32 v[32:33], v[32:33], v[40:41]
	v_pk_add_f32 v[30:31], v[30:31], v[38:39]
	v_pk_add_f32 v[28:29], v[28:29], v[36:37]
	v_pk_add_f32 v[26:27], v[26:27], v[34:35]
	s_and_b64 vcc, exec, s[6:7]
	v_lshl_add_u64 v[46:47], v[44:45], 2, s[18:19]
	s_cbranch_vccnz .LBB0_1537
	global_store_dwordx4 v[46:47], v[30:33], off nt
	global_store_dwordx4 v[46:47], v[26:29], off offset:16 nt
	s_cbranch_execnz .LBB0_1484

; __device__ __forceinline__ float bflo(unsigned u) { return __uint_as_float(u << 16); }
; __device__ __forceinline__ float bfhi(unsigned u) { return __uint_as_float(u & 0xffff0000u); }
; __device__ __forceinline__ unsigned pk2(float lo, float hi) { f32x2_t v = {lo, hi}; bf16x2_t b = __builtin_convertvector(v, bf16x2_t); return __builtin_bit_cast(unsigned, b); }
;     __device__ __forceinline__ void operator()(const f32x4 (&acc)[2][2][4][2], const pg8::Unit& u, int wr, int wc, int fr, int fq) const {
;     ...
;                     f32x4 x0, x1;
;                     if (xin) { x0 = *(const f32x4*)(xin + off); x1 = *(const f32x4*)(xin + off + 4); }
;                     else { const v4u xv = *(const v4u*)(xb + off); x0 = (f32x4){bflo(xv.x), bfhi(xv.x), bflo(xv.y), bfhi(xv.y)}; x1 = (f32x4){bflo(xv.z), bfhi(xv.z), bflo(xv.w), bfhi(xv.w)}; }
;                     const f32x4 n0 = x0 + acc[ai][bj][m][0], n1 = x1 + acc[ai][bj][m][1];
;                     if (xout) { *(f32x4*)(xout + off) = n0; *(f32x4*)(xout + off + 4) = n1; }
;                     else *(v4u*)(xb + off) = (v4u){pk2(n0[0], n0[1]), pk2(n0[2], n0[3]), pk2(n1[0], n1[1]), pk2(n1[2], n1[3])};
.LBB0_1487:
	s_waitcnt vmcnt(0)
	v_pk_add_f32 v[24:25], v[24:25], v[40:41]
	v_pk_add_f32 v[22:23], v[22:23], v[38:39]
	v_pk_add_f32 v[20:21], v[20:21], v[36:37]
	s_and_b64 vcc, exec, s[6:7]
	v_pk_add_f32 v[18:19], v[18:19], v[34:35]
	s_cbranch_vccnz .LBB0_1539
	global_store_dwordx4 v[46:47], v[22:25], off offset:512 nt
	global_store_dwordx4 v[46:47], v[18:21], off offset:528 nt
	s_cbranch_execnz .LBB0_1490

; __device__ __forceinline__ float bflo(unsigned u) { return __uint_as_float(u << 16); }
; __device__ __forceinline__ float bfhi(unsigned u) { return __uint_as_float(u & 0xffff0000u); }
; __device__ __forceinline__ unsigned pk2(float lo, float hi) { f32x2_t v = {lo, hi}; bf16x2_t b = __builtin_convertvector(v, bf16x2_t); return __builtin_bit_cast(unsigned, b); }
;     __device__ __forceinline__ void operator()(const f32x4 (&acc)[2][2][4][2], const pg8::Unit& u, int wr, int wc, int fr, int fq) const {
;     ...
;                     f32x4 x0, x1;
;                     if (xin) { x0 = *(const f32x4*)(xin + off); x1 = *(const f32x4*)(xin + off + 4); }
;                     else { const v4u xv = *(const v4u*)(xb + off); x0 = (f32x4){bflo(xv.x), bfhi(xv.x), bflo(xv.y), bfhi(xv.y)}; x1 = (f32x4){bflo(xv.z), bfhi(xv.z), bflo(xv.w), bfhi(xv.w)}; }
;                     const f32x4 n0 = x0 + acc[ai][bj][m][0], n1 = x1 + acc[ai][bj][m][1];
;                     if (xout) { *(f32x4*)(xout + off) = n0; *(f32x4*)(xout + off + 4) = n1; }
;                     else *(v4u*)(xb + off) = (v4u){pk2(n0[0], n0[1]), pk2(n0[2], n0[3]), pk2(n1[0], n1[1]), pk2(n1[2], n1[3])};
.LBB0_1497:
	s_waitcnt vmcnt(0)
	v_pk_add_f32 v[16:17], v[16:17], v[24:25]
	v_pk_add_f32 v[14:15], v[14:15], v[22:23]
	v_pk_add_f32 v[12:13], v[12:13], v[20:21]
	v_pk_add_f32 v[10:11], v[10:11], v[18:19]
	s_and_b64 vcc, exec, s[6:7]
	v_lshl_add_u64 v[30:31], v[28:29], 2, s[18:19]
	s_cbranch_vccnz .LBB0_1541
	global_store_dwordx4 v[30:31], v[14:17], off nt
	global_store_dwordx4 v[30:31], v[10:13], off offset:16 nt
	s_cbranch_execnz .LBB0_1500

; __device__ __forceinline__ float bflo(unsigned u) { return __uint_as_float(u << 16); }
; __device__ __forceinline__ float bfhi(unsigned u) { return __uint_as_float(u & 0xffff0000u); }
; __device__ __forceinline__ unsigned pk2(float lo, float hi) { f32x2_t v = {lo, hi}; bf16x2_t b = __builtin_convertvector(v, bf16x2_t); return __builtin_bit_cast(unsigned, b); }
;     __device__ __forceinline__ void operator()(const f32x4 (&acc)[2][2][4][2], const pg8::Unit& u, int wr, int wc, int fr, int fq) const {
;     ...
;                     f32x4 x0, x1;
;                     if (xin) { x0 = *(const f32x4*)(xin + off); x1 = *(const f32x4*)(xin + off + 4); }
;                     else { const v4u xv = *(const v4u*)(xb + off); x0 = (f32x4){bflo(xv.x), bfhi(xv.x), bflo(xv.y), bfhi(xv.y)}; x1 = (f32x4){bflo(xv.z), bfhi(xv.z), bflo(xv.w), bfhi(xv.w)}; }
;                     const f32x4 n0 = x0 + acc[ai][bj][m][0], n1 = x1 + acc[ai][bj][m][1];
;                     if (xout) { *(f32x4*)(xout + off) = n0; *(f32x4*)(xout + off + 4) = n1; }
;                     else *(v4u*)(xb + off) = (v4u){pk2(n0[0], n0[1]), pk2(n0[2], n0[3]), pk2(n1[0], n1[1]), pk2(n1[2], n1[3])};
.LBB0_1503:
	s_waitcnt vmcnt(0)
	v_pk_add_f32 v[8:9], v[8:9], v[24:25]
	v_pk_add_f32 v[6:7], v[6:7], v[22:23]
	v_pk_add_f32 v[4:5], v[4:5], v[20:21]
	s_and_b64 vcc, exec, s[6:7]
	v_pk_add_f32 v[2:3], v[2:3], v[18:19]
	s_cbranch_vccnz .LBB0_1543
	global_store_dwordx4 v[30:31], v[6:9], off offset:512 nt
	global_store_dwordx4 v[30:31], v[2:5], off offset:528 nt
	s_cbranch_execnz .LBB0_1506
